# mixA load balance: FNet dense-DFT (ctx) items reassigned from waves 1536-2047 to waves 0-511 (blocks that finish the mixer phase early)
# baseline (speedup 1.0000x reference)
.LBB0_669:
	s_or_b64 exec, exec, s[14:15]
	v_not_b32_e32 v2, v71
	v_cmp_gt_i32_e32 vcc, 0, v71
	v_mov_b32_e32 v71, 0x7000
	v_cndmask_b32_e32 v71, v71, v2, vcc
	v_add_u32_e32 v2, 0x800, v71
	v_cmp_lt_i32_e32 vcc, s24, v2
	v_lshlrev_b32_e32 v150, 4, v71
	s_or_b64 s[10:11], vcc, s[10:11]
	v_lshlrev_b32_e32 v151, 7, v71
	s_andn2_b64 exec, exec, s[10:11]
	s_cbranch_execz .LBB0_674

.LBB0_1561:
	s_or_b64 exec, exec, s[14:15]
	v_not_b32_e32 v2, v71
	v_cmp_gt_i32_e32 vcc, 0, v71
	v_mov_b32_e32 v71, 0x7000
	v_cndmask_b32_e32 v71, v71, v2, vcc
	v_add_u32_e32 v2, 0x800, v71
	v_cmp_lt_i32_e32 vcc, s24, v2
	v_lshlrev_b32_e32 v146, 4, v71
	s_or_b64 s[10:11], vcc, s[10:11]
	v_lshlrev_b32_e32 v147, 7, v71
	s_andn2_b64 exec, exec, s[10:11]
	s_cbranch_execz .LBB0_1566
